# a16 + ret_out: intra-chunk decay mask tabulated once per item per wave in LDS (same select-cvt-mul-exp sequence), ds_read_b32 lookups; jb loop unrolled and software-pipelined
# speedup vs baseline: 1.0133x; 1.0088x over previous
.LBB0_867:
	s_ashr_i32 s40, s8, 9
	s_ashr_i32 s41, s40, 31
	s_lshl_b32 s0, s8, 7
	s_and_b32 s0, s0, 0x1f80
	s_lshl_b64 s[40:41], s[40:41], 13
	s_or_b32 s0, s40, s0
	v_mov_b32_e32 v1, s41
	v_or_b32_e32 v0, s0, v120
	s_bfe_u32 s8, s8, 0x30006
	v_lshlrev_b64 v[126:127], 10, v[0:1]
	v_lshl_add_u64 v[0:1], s[10:11], 0, v[126:127]
	s_lshl_b32 s0, s8, 7
	v_lshl_add_u64 v[0:1], v[0:1], 0, s[0:1]
	v_lshl_add_u64 v[40:41], v[0:1], 0, v[108:109]
	global_load_dwordx4 v[88:91], v[40:41], off
	global_load_dwordx4 v[92:95], v[40:41], off offset:32
	s_lshl_b32 s8, s8, 2
	v_mov_b32_e32 v0, s8
	global_load_dword v128, v0, s[50:51]
	global_load_dword v129, v0, s[52:53]
	global_load_dwordx4 v[96:99], v[40:41], off offset:64
	ds_read_b128 v[0:3], v137 offset:53248
	ds_read_b128 v[32:35], v137 offset:53280
	ds_read_b128 v[16:19], v137 offset:57856
	ds_read_b128 v[36:39], v137 offset:57888
	global_load_dwordx4 v[100:103], v[40:41], off offset:96
	ds_read_b128 v[40:43], v137 offset:53312
	ds_read_b128 v[44:47], v137 offset:53344
	s_mov_b32 s35, 0
	s_waitcnt vmcnt(5) lgkmcnt(5)
	v_mfma_f32_32x32x16_bf16 v[0:15], v[0:3], v[88:91], 0
	s_waitcnt vmcnt(3)
	v_mul_f32_e32 v146, 0x3fb8aa3b, v128
	s_waitcnt vmcnt(2)
	v_mul_f32_e32 v147, 0x3fb8aa3b, v129
	v_fma_f32 v148, v128, s3, -v146
	v_rndne_f32_e32 v149, v146
	v_fma_f32 v150, v129, s3, -v147
	s_waitcnt lgkmcnt(3)
	v_mfma_f32_32x32x16_bf16 v[16:31], v[16:19], v[88:91], 0
	v_fmac_f32_e32 v148, 0x32a5705f, v128
	v_fmac_f32_e32 v150, 0x32a5705f, v129
	v_cmp_ngt_f32_e32 vcc, s42, v128
	v_mfma_f32_32x32x16_bf16 v[0:15], v[32:35], v[92:95], v[0:15]
	ds_read_b128 v[32:35], v137 offset:57920
	ds_read_b128 v[142:145], v137 offset:57952
	s_waitcnt lgkmcnt(4)
	v_mfma_f32_32x32x16_bf16 v[16:31], v[36:39], v[92:95], v[16:31]
	v_rndne_f32_e32 v36, v147
	v_sub_f32_e32 v37, v146, v149
	v_sub_f32_e32 v39, v147, v36
	v_add_f32_e32 v37, v37, v148
	v_cvt_i32_f32_e32 v38, v149
	v_add_f32_e32 v39, v39, v150
	v_exp_f32_e32 v37, v37
	s_waitcnt vmcnt(1) lgkmcnt(3)
	v_mfma_f32_32x32x16_bf16 v[0:15], v[40:43], v[96:99], v[0:15]
	v_cvt_i32_f32_e32 v36, v36
	v_exp_f32_e32 v39, v39
	v_ldexp_f32 v37, v37, v38
	ds_read_b128 v[146:149], v138
	ds_read_b128 v[150:153], v138 offset:32
	ds_read_b128 v[154:157], v138 offset:4608
	ds_read_b128 v[158:161], v138 offset:4640
	s_waitcnt lgkmcnt(5)
	v_mfma_f32_32x32x16_bf16 v[16:31], v[32:35], v[96:99], v[16:31]
	v_ldexp_f32 v32, v39, v36
	v_cndmask_b32_e32 v33, 0, v37, vcc
	v_cmp_ngt_f32_e32 vcc, s42, v129
	s_nop 1
	v_cndmask_b32_e32 v34, 0, v32, vcc
	v_cmp_nlt_f32_e32 vcc, s43, v128
	s_waitcnt vmcnt(0)
	v_mfma_f32_32x32x16_bf16 v[0:15], v[44:47], v[100:103], v[0:15]
	v_cndmask_b32_e32 v32, v141, v33, vcc
	v_cmp_nlt_f32_e32 vcc, s43, v129
	s_nop 1
	v_cndmask_b32_e32 v33, v141, v34, vcc
	v_mul_f32_e64 v128, v32, s22
	v_mul_f32_e64 v129, v33, s22
	s_waitcnt lgkmcnt(4)
	v_mfma_f32_32x32x16_bf16 v[16:31], v[142:145], v[100:103], v[16:31]
	v_mul_f32_e64 v162, v128, v122
	v_mul_f32_e64 v163, v129, v123
	v_mov_b32_e32 v142, v121
	v_sub_f32_e32 v32, v162, v163
	v_exp_f32_e32 v162, v32
	v_mov_b32_e32 v143, v133
	v_pk_mul_f32 v[32:33], v[162:163], v[0:1] op_sel_hi:[0,1]
	v_pk_mul_f32 v[46:47], v[162:163], v[14:15] op_sel_hi:[0,1]
	v_pk_mul_f32 v[44:45], v[162:163], v[12:13] op_sel_hi:[0,1]
	v_pk_mul_f32 v[42:43], v[162:163], v[10:11] op_sel_hi:[0,1]
	v_pk_mul_f32 v[40:41], v[162:163], v[8:9] op_sel_hi:[0,1]
	v_pk_mul_f32 v[38:39], v[162:163], v[6:7] op_sel_hi:[0,1]
	v_pk_mul_f32 v[36:37], v[162:163], v[4:5] op_sel_hi:[0,1]
	v_pk_mul_f32 v[34:35], v[162:163], v[2:3] op_sel_hi:[0,1]
	v_pk_mul_f32 v[0:1], v[162:163], v[16:17] op_sel_hi:[0,1]
	v_pk_mul_f32 v[14:15], v[162:163], v[30:31] op_sel_hi:[0,1]
	s_waitcnt lgkmcnt(3)
	v_mfma_f32_32x32x16_bf16 v[32:47], v[146:149], v[88:91], v[32:47]
	v_mul_f32_e64 v12, v162, v28
	v_mul_f32_e64 v13, v162, v29
	v_mul_f32_e64 v10, v162, v26
	v_mul_f32_e64 v11, v162, v27
	v_mul_f32_e64 v8, v162, v24
	v_mul_f32_e64 v9, v162, v25
	v_pk_mul_f32 v[6:7], v[162:163], v[22:23] op_sel_hi:[0,1]
	v_pk_mul_f32 v[4:5], v[162:163], v[20:21] op_sel_hi:[0,1]
	v_pk_mul_f32 v[2:3], v[162:163], v[18:19] op_sel_hi:[0,1]
	ds_read_b128 v[16:19], v138 offset:64
	ds_read_b128 v[20:23], v138 offset:96
	s_waitcnt lgkmcnt(3)
	v_mfma_f32_32x32x16_bf16 v[0:15], v[154:157], v[88:91], v[0:15]
	v_mfma_f32_32x32x16_bf16 v[32:47], v[150:153], v[92:95], v[32:47]
	s_waitcnt lgkmcnt(2)
	v_mfma_f32_32x32x16_bf16 v[0:15], v[158:161], v[92:95], v[0:15]
	s_waitcnt lgkmcnt(1)
	v_mfma_f32_32x32x16_bf16 v[32:47], v[16:19], v[96:99], v[32:47]
	ds_read_b128 v[16:19], v138 offset:4672
	ds_read_b128 v[24:27], v138 offset:4704
	s_waitcnt lgkmcnt(1)
	v_mfma_f32_32x32x16_bf16 v[0:15], v[16:19], v[96:99], v[0:15]
	v_exp_f32_e32 v16, v163
	v_mfma_f32_32x32x16_bf16 v[32:47], v[20:23], v[100:103], v[32:47]
	s_waitcnt lgkmcnt(0)
	v_mfma_f32_32x32x16_bf16 v[0:15], v[24:27], v[100:103], v[0:15]
	s_nop 9
	v_mul_f32_e64 v30, v16, v46
	v_mul_f32_e64 v31, v16, v47
	v_mul_f32_e64 v28, v16, v44
	v_mul_f32_e64 v29, v16, v45
	v_mul_f32_e64 v26, v16, v42
	v_mul_f32_e64 v27, v16, v43
	v_pk_mul_f32 v[24:25], v[16:17], v[40:41] op_sel_hi:[0,1]
	v_pk_mul_f32 v[22:23], v[16:17], v[38:39] op_sel_hi:[0,1]
	v_pk_mul_f32 v[20:21], v[16:17], v[36:37] op_sel_hi:[0,1]
	v_pk_mul_f32 v[18:19], v[16:17], v[34:35] op_sel_hi:[0,1]
	v_pk_mul_f32 v[14:15], v[16:17], v[14:15] op_sel_hi:[0,1]
	v_pk_mul_f32 v[12:13], v[16:17], v[12:13] op_sel_hi:[0,1]
	v_pk_mul_f32 v[10:11], v[16:17], v[10:11] op_sel_hi:[0,1]
	v_pk_mul_f32 v[8:9], v[16:17], v[8:9] op_sel_hi:[0,1]
	v_pk_mul_f32 v[6:7], v[16:17], v[6:7] op_sel_hi:[0,1]
	v_pk_mul_f32 v[4:5], v[16:17], v[4:5] op_sel_hi:[0,1]
	v_pk_mul_f32 v[2:3], v[16:17], v[2:3] op_sel_hi:[0,1]
	v_pk_mul_f32 v[0:1], v[16:17], v[0:1] op_sel_hi:[0,1]
	v_pk_mul_f32 v[16:17], v[16:17], v[32:33] op_sel_hi:[0,1]
	s_lshl_b32 s56, s33, 4
	s_add_i32 s56, s56, 0x18000
	v_and_b32_e32 v34, 63, v104
	v_sub_u32_e32 v35, 0x7f, v34
	v_subrev_u32_e32 v36, 63, v34
	v_sub_u32_e32 v37, 63, v34
	v_add_u32_e32 v38, 1, v34
	v_add_u32_e32 v39, 0x41, v34
	v_max_i32_e32 v37, v36, v37
	v_cmp_gt_i32_e32 vcc, 0, v36
	v_cvt_f32_u32_e32 v35, v35
	v_cvt_f32_u32_e32 v37, v37
	v_cvt_f32_u32_e32 v38, v38
	v_cvt_f32_u32_e32 v39, v39
	v_cndmask_b32_e32 v36, v128, v129, vcc
	v_mul_f32_e32 v35, v129, v35
	v_mul_f32_e32 v36, v36, v37
	v_mul_f32_e32 v38, v128, v38
	v_mul_f32_e32 v39, v128, v39
	v_exp_f32_e32 v35, v35
	v_exp_f32_e32 v36, v36
	v_exp_f32_e32 v38, v38
	v_exp_f32_e32 v39, v39
	v_lshl_add_u32 v40, v34, 2, s56
	v_add_u32_e32 v224, 4, v132
	v_lshl_add_u32 v224, v224, 2, s56
	ds_write_b32 v40, v35
	ds_write_b32 v40, v36 offset:256
	ds_write_b32 v40, v38 offset:512
	ds_write_b32 v40, v39 offset:768
	ds_read_b128 v[144:147], v142
	ds_read_b128 v[148:151], v142 offset:32
	ds_read_b128 v[152:155], v142 offset:64
	ds_read_b128 v[156:159], v142 offset:96
	ds_read_b32 v160, v224 offset:492
	ds_read_b32 v161, v224 offset:488
	ds_read_b32 v162, v224 offset:484
	ds_read_b32 v163, v224 offset:480
	ds_read_b32 v164, v224 offset:460
	ds_read_b32 v165, v224 offset:456
	ds_read_b32 v166, v224 offset:452
	ds_read_b32 v167, v224 offset:448
	ds_read_b32 v168, v224 offset:428
	ds_read_b32 v169, v224 offset:424
	ds_read_b32 v170, v224 offset:420
	ds_read_b32 v171, v224 offset:416
	ds_read_b32 v172, v224 offset:396
	ds_read_b32 v173, v224 offset:392
	ds_read_b32 v174, v224 offset:388
	ds_read_b32 v175, v224 offset:384
	s_waitcnt lgkmcnt(0)
	v_mfma_f32_32x32x16_bf16 v[32:47], v[144:147], v[88:91], 0
	v_mfma_f32_32x32x16_bf16 v[32:47], v[148:151], v[92:95], v[32:47]
	v_mfma_f32_32x32x16_bf16 v[32:47], v[152:155], v[96:99], v[32:47]
	v_mfma_f32_32x32x16_bf16 v[32:47], v[156:159], v[100:103], v[32:47]
	ds_read_b128 v[144:147], v142 offset:4608
	ds_read_b128 v[148:151], v142 offset:4640
	ds_read_b128 v[152:155], v142 offset:4672
	ds_read_b128 v[156:159], v142 offset:4704
	ds_read_b32 v176, v224 offset:364
	ds_read_b32 v177, v224 offset:360
	ds_read_b32 v178, v224 offset:356
	ds_read_b32 v179, v224 offset:352
	ds_read_b32 v180, v224 offset:332
	ds_read_b32 v181, v224 offset:328
	ds_read_b32 v182, v224 offset:324
	ds_read_b32 v183, v224 offset:320
	ds_read_b32 v184, v224 offset:300
	ds_read_b32 v185, v224 offset:296
	ds_read_b32 v186, v224 offset:292
	ds_read_b32 v187, v224 offset:288
	ds_read_b32 v188, v224 offset:268
	ds_read_b32 v189, v224 offset:264
	ds_read_b32 v190, v224 offset:260
	ds_read_b32 v191, v224 offset:256
	ds_read_b128 v[208:211], v143
	ds_read_b128 v[212:215], v143 offset:8704
	ds_read_b128 v[216:219], v143 offset:32
	ds_read_b128 v[220:223], v143 offset:8736
	s_waitcnt lgkmcnt(15)
	v_mfma_f32_32x32x16_bf16 v[192:207], v[144:147], v[88:91], 0
	v_mfma_f32_32x32x16_bf16 v[192:207], v[148:151], v[92:95], v[192:207]
	v_mfma_f32_32x32x16_bf16 v[192:207], v[152:155], v[96:99], v[192:207]
	v_mfma_f32_32x32x16_bf16 v[192:207], v[156:159], v[100:103], v[192:207]
	s_waitcnt lgkmcnt(0)
	v_pk_mul_f32 v[32:33], v[160:161], v[32:33]
	v_pk_mul_f32 v[34:35], v[162:163], v[34:35]
	v_pk_mul_f32 v[36:37], v[164:165], v[36:37]
	v_pk_mul_f32 v[38:39], v[166:167], v[38:39]
	v_pk_mul_f32 v[40:41], v[168:169], v[40:41]
	v_pk_mul_f32 v[42:43], v[170:171], v[42:43]
	v_pk_mul_f32 v[44:45], v[172:173], v[44:45]
	v_pk_mul_f32 v[46:47], v[174:175], v[46:47]
	v_cvt_pk_bf16_f32 v240, v32, v33
	v_cvt_pk_bf16_f32 v241, v34, v35
	v_cvt_pk_bf16_f32 v242, v36, v37
	v_cvt_pk_bf16_f32 v243, v38, v39
	v_cvt_pk_bf16_f32 v244, v40, v41
	v_cvt_pk_bf16_f32 v245, v42, v43
	v_cvt_pk_bf16_f32 v246, v44, v45
	v_cvt_pk_bf16_f32 v247, v46, v47
	s_nop 1
	v_mfma_f32_32x32x16_bf16 v[16:31], v[208:211], v[240:243], v[16:31]
	v_mfma_f32_32x32x16_bf16 v[0:15], v[212:215], v[240:243], v[0:15]
	v_mfma_f32_32x32x16_bf16 v[16:31], v[216:219], v[244:247], v[16:31]
	v_mfma_f32_32x32x16_bf16 v[0:15], v[220:223], v[244:247], v[0:15]
	ds_read_b128 v[144:147], v142 offset:9216
	ds_read_b128 v[148:151], v142 offset:9248
	ds_read_b128 v[152:155], v142 offset:9280
	ds_read_b128 v[156:159], v142 offset:9312
	ds_read_b32 v160, v224 offset:236
	ds_read_b32 v161, v224 offset:232
	ds_read_b32 v162, v224 offset:228
	ds_read_b32 v163, v224 offset:224
	ds_read_b32 v164, v224 offset:204
	ds_read_b32 v165, v224 offset:200
	ds_read_b32 v166, v224 offset:196
	ds_read_b32 v167, v224 offset:192
	ds_read_b32 v168, v224 offset:172
	ds_read_b32 v169, v224 offset:168
	ds_read_b32 v170, v224 offset:164
	ds_read_b32 v171, v224 offset:160
	ds_read_b32 v172, v224 offset:140
	ds_read_b32 v173, v224 offset:136
	ds_read_b32 v174, v224 offset:132
	ds_read_b32 v175, v224 offset:128
	ds_read_b128 v[208:211], v143 offset:64
	ds_read_b128 v[212:215], v143 offset:8768
	ds_read_b128 v[216:219], v143 offset:96
	ds_read_b128 v[220:223], v143 offset:8800
	s_waitcnt lgkmcnt(15)
	v_mfma_f32_32x32x16_bf16 v[32:47], v[144:147], v[88:91], 0
	v_mfma_f32_32x32x16_bf16 v[32:47], v[148:151], v[92:95], v[32:47]
	v_mfma_f32_32x32x16_bf16 v[32:47], v[152:155], v[96:99], v[32:47]
	v_mfma_f32_32x32x16_bf16 v[32:47], v[156:159], v[100:103], v[32:47]
	s_waitcnt lgkmcnt(0)
	v_pk_mul_f32 v[192:193], v[176:177], v[192:193]
	v_pk_mul_f32 v[194:195], v[178:179], v[194:195]
	v_pk_mul_f32 v[196:197], v[180:181], v[196:197]
	v_pk_mul_f32 v[198:199], v[182:183], v[198:199]
	v_pk_mul_f32 v[200:201], v[184:185], v[200:201]
	v_pk_mul_f32 v[202:203], v[186:187], v[202:203]
	v_pk_mul_f32 v[204:205], v[188:189], v[204:205]
	v_pk_mul_f32 v[206:207], v[190:191], v[206:207]
	v_cvt_pk_bf16_f32 v240, v192, v193
	v_cvt_pk_bf16_f32 v241, v194, v195
	v_cvt_pk_bf16_f32 v242, v196, v197
	v_cvt_pk_bf16_f32 v243, v198, v199
	v_cvt_pk_bf16_f32 v244, v200, v201
	v_cvt_pk_bf16_f32 v245, v202, v203
	v_cvt_pk_bf16_f32 v246, v204, v205
	v_cvt_pk_bf16_f32 v247, v206, v207
	s_nop 1
	v_mfma_f32_32x32x16_bf16 v[16:31], v[208:211], v[240:243], v[16:31]
	v_mfma_f32_32x32x16_bf16 v[0:15], v[212:215], v[240:243], v[0:15]
	v_mfma_f32_32x32x16_bf16 v[16:31], v[216:219], v[244:247], v[16:31]
	v_mfma_f32_32x32x16_bf16 v[0:15], v[220:223], v[244:247], v[0:15]
	ds_read_b128 v[144:147], v142 offset:13824
	ds_read_b128 v[148:151], v142 offset:13856
	ds_read_b128 v[152:155], v142 offset:13888
	ds_read_b128 v[156:159], v142 offset:13920
	ds_read_b32 v176, v224 offset:108
	ds_read_b32 v177, v224 offset:104
	ds_read_b32 v178, v224 offset:100
	ds_read_b32 v179, v224 offset:96
	ds_read_b32 v180, v224 offset:76
	ds_read_b32 v181, v224 offset:72
	ds_read_b32 v182, v224 offset:68
	ds_read_b32 v183, v224 offset:64
	ds_read_b32 v184, v224 offset:44
	ds_read_b32 v185, v224 offset:40
	ds_read_b32 v186, v224 offset:36
	ds_read_b32 v187, v224 offset:32
	ds_read_b32 v188, v224 offset:12
	ds_read_b32 v189, v224 offset:8
	ds_read_b32 v190, v224 offset:4
	ds_read_b32 v191, v224
	ds_read_b128 v[208:211], v143 offset:128
	ds_read_b128 v[212:215], v143 offset:8832
	ds_read_b128 v[216:219], v143 offset:160
	ds_read_b128 v[220:223], v143 offset:8864
	s_waitcnt lgkmcnt(15)
	v_mfma_f32_32x32x16_bf16 v[192:207], v[144:147], v[88:91], 0
	v_mfma_f32_32x32x16_bf16 v[192:207], v[148:151], v[92:95], v[192:207]
	v_mfma_f32_32x32x16_bf16 v[192:207], v[152:155], v[96:99], v[192:207]
	v_mfma_f32_32x32x16_bf16 v[192:207], v[156:159], v[100:103], v[192:207]
	s_waitcnt lgkmcnt(0)
	v_pk_mul_f32 v[32:33], v[160:161], v[32:33]
	v_pk_mul_f32 v[34:35], v[162:163], v[34:35]
	v_pk_mul_f32 v[36:37], v[164:165], v[36:37]
	v_pk_mul_f32 v[38:39], v[166:167], v[38:39]
	v_pk_mul_f32 v[40:41], v[168:169], v[40:41]
	v_pk_mul_f32 v[42:43], v[170:171], v[42:43]
	v_pk_mul_f32 v[44:45], v[172:173], v[44:45]
	v_pk_mul_f32 v[46:47], v[174:175], v[46:47]
	v_cvt_pk_bf16_f32 v240, v32, v33
	v_cvt_pk_bf16_f32 v241, v34, v35
	v_cvt_pk_bf16_f32 v242, v36, v37
	v_cvt_pk_bf16_f32 v243, v38, v39
	v_cvt_pk_bf16_f32 v244, v40, v41
	v_cvt_pk_bf16_f32 v245, v42, v43
	v_cvt_pk_bf16_f32 v246, v44, v45
	v_cvt_pk_bf16_f32 v247, v46, v47
	s_nop 1
	v_mfma_f32_32x32x16_bf16 v[16:31], v[208:211], v[240:243], v[16:31]
	v_mfma_f32_32x32x16_bf16 v[0:15], v[212:215], v[240:243], v[0:15]
	v_mfma_f32_32x32x16_bf16 v[16:31], v[216:219], v[244:247], v[16:31]
	v_mfma_f32_32x32x16_bf16 v[0:15], v[220:223], v[244:247], v[0:15]
	ds_read_b128 v[208:211], v143 offset:192
	ds_read_b128 v[212:215], v143 offset:8896
	ds_read_b128 v[216:219], v143 offset:224
	ds_read_b128 v[220:223], v143 offset:8928
	s_waitcnt lgkmcnt(0)
	v_pk_mul_f32 v[192:193], v[176:177], v[192:193]
	v_pk_mul_f32 v[194:195], v[178:179], v[194:195]
	v_pk_mul_f32 v[196:197], v[180:181], v[196:197]
	v_pk_mul_f32 v[198:199], v[182:183], v[198:199]
	v_pk_mul_f32 v[200:201], v[184:185], v[200:201]
	v_pk_mul_f32 v[202:203], v[186:187], v[202:203]
	v_pk_mul_f32 v[204:205], v[188:189], v[204:205]
	v_pk_mul_f32 v[206:207], v[190:191], v[206:207]
	v_cvt_pk_bf16_f32 v240, v192, v193
	v_cvt_pk_bf16_f32 v241, v194, v195
	v_cvt_pk_bf16_f32 v242, v196, v197
	v_cvt_pk_bf16_f32 v243, v198, v199
	v_cvt_pk_bf16_f32 v244, v200, v201
	v_cvt_pk_bf16_f32 v245, v202, v203
	v_cvt_pk_bf16_f32 v246, v204, v205
	v_cvt_pk_bf16_f32 v247, v206, v207
	s_nop 1
	v_mfma_f32_32x32x16_bf16 v[16:31], v[208:211], v[240:243], v[16:31]
	v_mfma_f32_32x32x16_bf16 v[0:15], v[212:215], v[240:243], v[0:15]
	v_mfma_f32_32x32x16_bf16 v[16:31], v[216:219], v[244:247], v[16:31]
	v_mfma_f32_32x32x16_bf16 v[0:15], v[220:223], v[244:247], v[0:15]
	s_movk_i32 s35, 0xff80
	s_nop 3
	s_nop 6
	v_mul_f32_e32 v32, v17, v17
	v_fmac_f32_e32 v32, v16, v16
	v_fmac_f32_e32 v32, v18, v18
	v_fmac_f32_e32 v32, v19, v19
	v_fmac_f32_e32 v32, v20, v20
	v_fmac_f32_e32 v32, v21, v21
	v_fmac_f32_e32 v32, v22, v22
	v_fmac_f32_e32 v32, v23, v23
	v_fmac_f32_e32 v32, v24, v24
	v_fmac_f32_e32 v32, v25, v25
	v_fmac_f32_e32 v32, v26, v26
	v_fmac_f32_e32 v32, v27, v27
	v_fmac_f32_e32 v32, v28, v28
	v_fmac_f32_e32 v32, v29, v29
	v_fmac_f32_e32 v32, v30, v30
	v_fmac_f32_e32 v32, v31, v31
	v_fmac_f32_e32 v32, v0, v0
	v_fmac_f32_e32 v32, v1, v1
	v_fmac_f32_e32 v32, v2, v2
	v_fmac_f32_e32 v32, v3, v3
	v_fmac_f32_e32 v32, v4, v4
	v_fmac_f32_e32 v32, v5, v5
	v_fmac_f32_e32 v32, v6, v6
	v_fmac_f32_e32 v32, v7, v7
	v_fmac_f32_e32 v32, v8, v8
	v_fmac_f32_e32 v32, v9, v9
	v_fmac_f32_e32 v32, v10, v10
	v_fmac_f32_e32 v32, v11, v11
	v_fmac_f32_e32 v32, v12, v12
	v_fmac_f32_e32 v32, v13, v13
	v_fmac_f32_e32 v32, v14, v14
	v_fmac_f32_e32 v32, v15, v15
	v_mov_b32_e32 v33, v32
	s_nop 1
	v_permlane32_swap_b32_e32 v32, v33
	v_add_f32_e32 v36, v32, v33
	s_and_saveexec_b64 s[40:41], s[6:7]
	s_cbranch_execz .LBB0_864
	ds_write_b32 v139, v36
	s_branch .LBB0_864
